# combined-trims version with coalesced LDS waits
# baseline (speedup 1.0000x reference)
.Lmy_ck_nz:
	s_mov_b32 s100, 0xe000
	s_cmp_eq_u32 s23, 0
	s_cselect_b32 s100, 0x1c000, s100
	s_mov_b32 s101, 0x12e00
	s_cselect_b32 s101, 0x22100, s101
	s_lshl_b32 s96, s23, 13
	s_add_i32 s97, s96, 0x18000
	s_add_i32 s96, s96, 0xa000
	v_add_u32_e32 v225, s100, v1
	v_add_u32_e32 v236, s100, v0
	v_add_u32_e32 v34, s100, v10
	v_add_u32_e32 v226, s100, v2
	v_add_u32_e32 v227, s100, v3
	v_add_u32_e32 v228, s100, v4
	v_add_u32_e32 v229, s100, v5
	v_add_u32_e32 v237, s100, v6
	v_add_u32_e32 v238, s100, v7
	v_add_u32_e32 v230, s96, v8
	v_add_u32_e32 v239, s96, v9
	v_add_u32_e32 v231, s97, v8
	v_add_u32_e32 v26, s101, v1
	v_add_u32_e32 v27, s101, v0
	v_add_u32_e32 v35, s101, v10
	v_add_u32_e32 v28, s101, v2
	v_add_u32_e32 v29, s101, v3
	v_add_u32_e32 v30, s101, v4
	v_add_u32_e32 v31, s101, v5
	v_add_u32_e32 v32, s101, v6
	v_add_u32_e32 v33, s101, v7
	ds_read_b64 v[80:81], v237
	ds_read_b64 v[82:83], v238
	ds_read_b32 v36, v239
	ds_read_b32 v37, v239 offset:256
	ds_read_b128 v[88:91], v225
	ds_read_b128 v[92:95], v225 offset:1024
	ds_read_b128 v[96:99], v225 offset:2048
	ds_read_b128 v[100:103], v225 offset:3072
	ds_read_b32 v104, v227 offset:4
	ds_read_b32 v105, v227 offset:76
	ds_read_b64 v[106:107], v227 offset:8
	ds_read_b64 v[108:109], v227 offset:40
	ds_read_b32 v126, v229 offset:4
	ds_read_b32 v127, v229 offset:76
	ds_read_b64 v[128:129], v229 offset:8
	ds_read_b64 v[130:131], v229 offset:40
	ds_read_b64 v[110:111], v228
	ds_read_b64 v[112:113], v228 offset:32
	ds_read_b64 v[114:115], v228 offset:64
	ds_read_b64 v[116:117], v228 offset:96
	ds_read_b64 v[118:119], v228 offset:8
	ds_read_b64 v[120:121], v228 offset:40
	ds_read_b64 v[122:123], v228 offset:72
	ds_read_b64 v[124:125], v228 offset:104
	s_waitcnt lgkmcnt(15)
	v_mfma_f32_16x16x4_f32 v[240:243], v80, v36, 0
	v_mfma_f32_16x16x4_f32 v[240:243], v81, v37, v[240:243]
	v_mfma_f32_16x16x4_f32 v[240:243], v88, v208, v[240:243]
	ds_read_b64 v[186:187], v34
	ds_read_b64 v[190:191], v34 offset:1024
	v_mfma_f32_16x16x4_f32 v[244:247], v89, v209, 0
	ds_read_b64 v[194:195], v34 offset:2048
	ds_read_b64 v[198:199], v34 offset:3072
	v_mfma_f32_16x16x4_f32 v[240:243], v90, v210, v[240:243]
	ds_read_b64 v[184:185], v236
	ds_read_b64 v[188:189], v236 offset:1024
	ds_read_b64 v[132:133], v237 offset:9984
	v_mfma_f32_16x16x4_f32 v[244:247], v91, v211, v[244:247]
	ds_read_b64 v[134:135], v238 offset:9984
	ds_read_b64 v[192:193], v236 offset:2048
	ds_read_b64 v[196:197], v236 offset:3072
	v_mfma_f32_16x16x4_f32 v[240:243], v92, v212, v[240:243]
	ds_read_b32 v38, v239 offset:2048
	ds_read_b32 v39, v239 offset:2304
	ds_read_b128 v[140:143], v225 offset:9984
	v_mfma_f32_16x16x4_f32 v[244:247], v93, v213, v[244:247]
	ds_read_b128 v[144:147], v225 offset:11008
	ds_read_b128 v[148:151], v225 offset:12032
	ds_read_b128 v[152:155], v225 offset:13056
	v_mfma_f32_16x16x4_f32 v[240:243], v94, v214, v[240:243]
	ds_read_b32 v156, v227 offset:9988
	ds_read_b32 v157, v227 offset:10060
	v_mfma_f32_16x16x4_f32 v[244:247], v95, v215, v[244:247]
	ds_read_b64 v[158:159], v227 offset:9992
	ds_read_b64 v[160:161], v227 offset:10024
	v_mfma_f32_16x16x4_f32 v[240:243], v96, v216, v[240:243]
	ds_read_b32 v178, v229 offset:9988
	ds_read_b32 v179, v229 offset:10060
	v_mfma_f32_16x16x4_f32 v[244:247], v97, v217, v[244:247]
	ds_read_b64 v[180:181], v229 offset:9992
	ds_read_b64 v[182:183], v229 offset:10024
	v_mfma_f32_16x16x4_f32 v[240:243], v98, v218, v[240:243]
	ds_read_b64 v[162:163], v228 offset:9984
	ds_read_b64 v[164:165], v228 offset:10016
	v_mfma_f32_16x16x4_f32 v[244:247], v99, v219, v[244:247]
	ds_read_b64 v[166:167], v228 offset:10048
	ds_read_b64 v[168:169], v228 offset:10080
	v_mfma_f32_16x16x4_f32 v[240:243], v100, v220, v[240:243]
	ds_read_b64 v[170:171], v228 offset:9992
	ds_read_b64 v[172:173], v228 offset:10024
	v_mfma_f32_16x16x4_f32 v[244:247], v101, v221, v[244:247]
	ds_read_b64 v[174:175], v228 offset:10056
	ds_read_b64 v[176:177], v228 offset:10088
	v_mfma_f32_16x16x4_f32 v[240:243], v102, v222, v[240:243]
	v_mfma_f32_16x16x4_f32 v[244:247], v103, v223, v[244:247]
	s_waitcnt lgkmcnt(14)
	v_mfma_f32_16x16x4_f32 v[208:211], v186, v36, v[208:211]
	v_mfma_f32_16x16x4_f32 v[212:215], v190, v36, v[212:215]
	v_pk_add_f32 v[240:241], v[240:241], v[244:245]
	v_pk_add_f32 v[242:243], v[242:243], v[246:247]
	v_fmac_f32_e32 v241, v104, v240
	v_mfma_f32_16x16x4_f32 v[216:219], v194, v36, v[216:219]
	v_pk_fma_f32 v[242:243], v[106:107], v[240:241], v[242:243] op_sel:[0,0,0] op_sel_hi:[1,0,1]
	v_pk_fma_f32 v[242:243], v[108:109], v[240:241], v[242:243] op_sel:[0,1,0] op_sel_hi:[1,1,1]
	v_fmac_f32_e32 v243, v105, v242
	v_mfma_f32_16x16x4_f32 v[72:75], v132, v38, 0
	ds_bpermute_b32 v204, v232, v240
	ds_bpermute_b32 v205, v232, v241
	ds_bpermute_b32 v206, v232, v242
	v_mfma_f32_16x16x4_f32 v[72:75], v133, v39, v[72:75]
	ds_bpermute_b32 v207, v232, v243
	s_waitcnt lgkmcnt(2)
	v_pk_fma_f32 v[240:241], v[110:111], v[204:205], v[240:241] op_sel:[0,0,0] op_sel_hi:[1,0,1]
	v_pk_fma_f32 v[240:241], v[112:113], v[204:205], v[240:241] op_sel:[0,1,0] op_sel_hi:[1,1,1]
	v_mfma_f32_16x16x4_f32 v[220:223], v198, v36, v[220:223]
	s_waitcnt lgkmcnt(0)
	v_pk_fma_f32 v[240:241], v[114:115], v[206:207], v[240:241] op_sel:[0,0,0] op_sel_hi:[1,0,1]
	v_pk_fma_f32 v[240:241], v[116:117], v[206:207], v[240:241] op_sel:[0,1,0] op_sel_hi:[1,1,1]
	v_pk_fma_f32 v[242:243], v[118:119], v[204:205], v[242:243] op_sel:[0,0,0] op_sel_hi:[1,0,1]
	v_mfma_f32_16x16x4_f32 v[208:211], v187, v37, v[208:211]
	v_pk_fma_f32 v[242:243], v[120:121], v[204:205], v[242:243] op_sel:[0,1,0] op_sel_hi:[1,1,1]
	v_pk_fma_f32 v[242:243], v[122:123], v[206:207], v[242:243] op_sel:[0,0,0] op_sel_hi:[1,0,1]
	v_pk_fma_f32 v[242:243], v[124:125], v[206:207], v[242:243] op_sel:[0,1,0] op_sel_hi:[1,1,1]
	v_mfma_f32_16x16x4_f32 v[212:215], v191, v37, v[212:215]
	v_fmac_f32_e32 v241, v126, v240
	v_pk_fma_f32 v[242:243], v[128:129], v[240:241], v[242:243] op_sel:[0,0,0] op_sel_hi:[1,0,1]
	v_pk_fma_f32 v[242:243], v[130:131], v[240:241], v[242:243] op_sel:[0,1,0] op_sel_hi:[1,1,1]
	v_mfma_f32_16x16x4_f32 v[216:219], v195, v37, v[216:219]
	v_fmac_f32_e32 v243, v127, v242
	v_mov_b32_e32 v252, v240
	v_mov_b32_e32 v253, v241
	v_mfma_f32_16x16x4_f32 v[220:223], v199, v37, v[220:223]
	v_mov_b32_e32 v254, v242
	v_mov_b32_e32 v255, v243
	s_nop 0
	v_permlane32_swap_b32_e32 v252, v254
	v_permlane32_swap_b32_e32 v253, v255
	s_nop 0
	v_mfma_f32_16x16x4_f32 v[248:251], v82, v252, v[240:243]
	v_mfma_f32_16x16x4_f32 v[248:251], v83, v253, v[248:251]
	v_mfma_f32_16x16x4_f32 v[208:211], v184, v252, v[208:211]
	ds_read_b128 v[88:91], v226
	v_mfma_f32_16x16x4_f32 v[212:215], v188, v252, v[212:215]
	ds_read_b128 v[92:95], v226 offset:64
	v_mfma_f32_16x16x4_f32 v[216:219], v192, v252, v[216:219]
	ds_read_b128 v[96:99], v226 offset:128
	v_mfma_f32_16x16x4_f32 v[220:223], v196, v252, v[220:223]
	ds_read_b128 v[100:103], v226 offset:192
	v_mfma_f32_16x16x4_f32 v[208:211], v185, v253, v[208:211]
	s_mov_b64 exec, s[98:99]
	ds_write_b32 v231, v248
	ds_write_b32 v231, v249 offset:256
	ds_write_b32 v231, v250 offset:512
	ds_write_b32 v231, v251 offset:768
	s_mov_b64 exec, -1
	v_mfma_f32_16x16x4_f32 v[212:215], v189, v253, v[212:215]
	v_mfma_f32_16x16x4_f32 v[216:219], v193, v253, v[216:219]
	v_mfma_f32_16x16x4_f32 v[220:223], v197, v253, v[220:223]
	s_waitcnt lgkmcnt(7)
	v_pk_mul_f32 v[208:209], v[208:209], v[88:89]
	v_pk_mul_f32 v[210:211], v[210:211], v[90:91]
	s_nop 0
	v_mfma_f32_16x16x4_f32 v[72:75], v140, v208, v[72:75]
	s_waitcnt lgkmcnt(6)
	v_pk_mul_f32 v[212:213], v[212:213], v[92:93]
	v_mfma_f32_16x16x4_f32 v[244:247], v141, v209, 0
	v_pk_mul_f32 v[214:215], v[214:215], v[94:95]
	v_mfma_f32_16x16x4_f32 v[72:75], v142, v210, v[72:75]
	s_waitcnt lgkmcnt(5)
	v_pk_mul_f32 v[216:217], v[216:217], v[96:97]
	v_mfma_f32_16x16x4_f32 v[244:247], v143, v211, v[244:247]
	v_pk_mul_f32 v[218:219], v[218:219], v[98:99]
	v_mfma_f32_16x16x4_f32 v[72:75], v144, v212, v[72:75]
	s_waitcnt lgkmcnt(4)
	v_pk_mul_f32 v[220:221], v[220:221], v[100:101]
	v_mfma_f32_16x16x4_f32 v[244:247], v145, v213, v[244:247]
	v_pk_mul_f32 v[222:223], v[222:223], v[102:103]
	v_mfma_f32_16x16x4_f32 v[72:75], v146, v214, v[72:75]
	ds_read_b64 v[186:187], v34 offset:9984
	ds_read_b64 v[190:191], v34 offset:11008
	v_mfma_f32_16x16x4_f32 v[244:247], v147, v215, v[244:247]
	ds_read_b64 v[194:195], v34 offset:12032
	ds_read_b64 v[198:199], v34 offset:13056
	v_mfma_f32_16x16x4_f32 v[72:75], v148, v216, v[72:75]
	ds_read_b64 v[184:185], v236 offset:9984
	ds_read_b64 v[188:189], v236 offset:11008
	ds_read_b64 v[80:81], v32
	v_mfma_f32_16x16x4_f32 v[244:247], v149, v217, v[244:247]
	ds_read_b64 v[82:83], v33
	ds_read_b32 v36, v239 offset:4096
	ds_read_b64 v[192:193], v236 offset:12032
	v_mfma_f32_16x16x4_f32 v[72:75], v150, v218, v[72:75]
	ds_read_b64 v[196:197], v236 offset:13056
	ds_read_b32 v37, v239 offset:4352
	ds_read_b128 v[88:91], v26
	v_mfma_f32_16x16x4_f32 v[244:247], v151, v219, v[244:247]
	ds_read_b128 v[92:95], v26 offset:1024
	ds_read_b128 v[96:99], v26 offset:2048
	ds_read_b128 v[100:103], v26 offset:3072
	v_mfma_f32_16x16x4_f32 v[72:75], v152, v220, v[72:75]
	ds_read_b32 v104, v29 offset:4
	ds_read_b32 v105, v29 offset:76
	ds_read_b64 v[106:107], v29 offset:8
	v_mfma_f32_16x16x4_f32 v[244:247], v153, v221, v[244:247]
	ds_read_b64 v[108:109], v29 offset:40
	ds_read_b32 v126, v31 offset:4
	ds_read_b32 v127, v31 offset:76
	v_mfma_f32_16x16x4_f32 v[72:75], v154, v222, v[72:75]
	ds_read_b64 v[128:129], v31 offset:8
	ds_read_b64 v[130:131], v31 offset:40
	ds_read_b64 v[110:111], v30
	v_mfma_f32_16x16x4_f32 v[244:247], v155, v223, v[244:247]
	ds_read_b64 v[112:113], v30 offset:32
	ds_read_b64 v[114:115], v30 offset:64
	ds_read_b64 v[116:117], v30 offset:96
	ds_read_b64 v[118:119], v30 offset:8
	ds_read_b64 v[120:121], v30 offset:40
	ds_read_b64 v[122:123], v30 offset:72
	ds_read_b64 v[124:125], v30 offset:104
	s_waitcnt lgkmcnt(15)
	v_mfma_f32_16x16x4_f32 v[208:211], v186, v38, v[208:211]
	v_mfma_f32_16x16x4_f32 v[212:215], v190, v38, v[212:215]
	v_pk_add_f32 v[72:73], v[72:73], v[244:245]
	v_pk_add_f32 v[74:75], v[74:75], v[246:247]
	v_fmac_f32_e32 v73, v156, v72
	v_mfma_f32_16x16x4_f32 v[216:219], v194, v38, v[216:219]
	v_pk_fma_f32 v[74:75], v[158:159], v[72:73], v[74:75] op_sel:[0,0,0] op_sel_hi:[1,0,1]
	v_pk_fma_f32 v[74:75], v[160:161], v[72:73], v[74:75] op_sel:[0,1,0] op_sel_hi:[1,1,1]
	v_fmac_f32_e32 v75, v157, v74
	v_mfma_f32_16x16x4_f32 v[240:243], v80, v36, 0
	ds_bpermute_b32 v204, v232, v72
	ds_bpermute_b32 v205, v232, v73
	ds_bpermute_b32 v206, v232, v74
	v_mfma_f32_16x16x4_f32 v[240:243], v81, v37, v[240:243]
	ds_bpermute_b32 v207, v232, v75
	s_waitcnt lgkmcnt(2)
	v_pk_fma_f32 v[72:73], v[162:163], v[204:205], v[72:73] op_sel:[0,0,0] op_sel_hi:[1,0,1]
	v_pk_fma_f32 v[72:73], v[164:165], v[204:205], v[72:73] op_sel:[0,1,0] op_sel_hi:[1,1,1]
	v_mfma_f32_16x16x4_f32 v[220:223], v198, v38, v[220:223]
	s_waitcnt lgkmcnt(0)
	v_pk_fma_f32 v[72:73], v[166:167], v[206:207], v[72:73] op_sel:[0,0,0] op_sel_hi:[1,0,1]
	v_pk_fma_f32 v[72:73], v[168:169], v[206:207], v[72:73] op_sel:[0,1,0] op_sel_hi:[1,1,1]
	v_pk_fma_f32 v[74:75], v[170:171], v[204:205], v[74:75] op_sel:[0,0,0] op_sel_hi:[1,0,1]
	v_mfma_f32_16x16x4_f32 v[208:211], v187, v39, v[208:211]
	v_pk_fma_f32 v[74:75], v[172:173], v[204:205], v[74:75] op_sel:[0,1,0] op_sel_hi:[1,1,1]
	v_pk_fma_f32 v[74:75], v[174:175], v[206:207], v[74:75] op_sel:[0,0,0] op_sel_hi:[1,0,1]
	v_pk_fma_f32 v[74:75], v[176:177], v[206:207], v[74:75] op_sel:[0,1,0] op_sel_hi:[1,1,1]
	v_mfma_f32_16x16x4_f32 v[212:215], v191, v39, v[212:215]
	v_fmac_f32_e32 v73, v178, v72
	v_pk_fma_f32 v[74:75], v[180:181], v[72:73], v[74:75] op_sel:[0,0,0] op_sel_hi:[1,0,1]
	v_pk_fma_f32 v[74:75], v[182:183], v[72:73], v[74:75] op_sel:[0,1,0] op_sel_hi:[1,1,1]
	v_mfma_f32_16x16x4_f32 v[216:219], v195, v39, v[216:219]
	v_fmac_f32_e32 v75, v179, v74
	v_mov_b32_e32 v252, v72
	v_mov_b32_e32 v253, v73
	v_mfma_f32_16x16x4_f32 v[220:223], v199, v39, v[220:223]
	v_mov_b32_e32 v254, v74
	v_mov_b32_e32 v255, v75
	s_nop 0
	v_permlane32_swap_b32_e32 v252, v254
	v_permlane32_swap_b32_e32 v253, v255
	s_nop 0
	v_mfma_f32_16x16x4_f32 v[248:251], v134, v252, v[72:75]
	v_mfma_f32_16x16x4_f32 v[248:251], v135, v253, v[248:251]
	v_mfma_f32_16x16x4_f32 v[208:211], v184, v252, v[208:211]
	ds_read_b128 v[140:143], v226 offset:9984
	v_mfma_f32_16x16x4_f32 v[212:215], v188, v252, v[212:215]
	ds_read_b128 v[144:147], v226 offset:10048
	v_mfma_f32_16x16x4_f32 v[216:219], v192, v252, v[216:219]
	ds_read_b128 v[148:151], v226 offset:10112
	v_mfma_f32_16x16x4_f32 v[220:223], v196, v252, v[220:223]
	ds_read_b128 v[152:155], v226 offset:10176
	v_mfma_f32_16x16x4_f32 v[208:211], v185, v253, v[208:211]
	s_mov_b64 exec, s[98:99]
	ds_write_b32 v231, v248 offset:2048
	ds_write_b32 v231, v249 offset:2304
	ds_write_b32 v231, v250 offset:2560
	ds_write_b32 v231, v251 offset:2816
	s_mov_b64 exec, -1
	v_mfma_f32_16x16x4_f32 v[212:215], v189, v253, v[212:215]
	v_mfma_f32_16x16x4_f32 v[216:219], v193, v253, v[216:219]
	v_mfma_f32_16x16x4_f32 v[220:223], v197, v253, v[220:223]
	s_waitcnt lgkmcnt(7)
	v_pk_mul_f32 v[208:209], v[208:209], v[140:141]
	v_pk_mul_f32 v[210:211], v[210:211], v[142:143]
	s_nop 0
	v_mfma_f32_16x16x4_f32 v[240:243], v88, v208, v[240:243]
	s_waitcnt lgkmcnt(6)
	v_pk_mul_f32 v[212:213], v[212:213], v[144:145]
	v_mfma_f32_16x16x4_f32 v[244:247], v89, v209, 0
	v_pk_mul_f32 v[214:215], v[214:215], v[146:147]
	v_mfma_f32_16x16x4_f32 v[240:243], v90, v210, v[240:243]
	s_waitcnt lgkmcnt(5)
	v_pk_mul_f32 v[216:217], v[216:217], v[148:149]
	v_mfma_f32_16x16x4_f32 v[244:247], v91, v211, v[244:247]
	v_pk_mul_f32 v[218:219], v[218:219], v[150:151]
	v_mfma_f32_16x16x4_f32 v[240:243], v92, v212, v[240:243]
	s_waitcnt lgkmcnt(4)
	v_pk_mul_f32 v[220:221], v[220:221], v[152:153]
	v_mfma_f32_16x16x4_f32 v[244:247], v93, v213, v[244:247]
	v_pk_mul_f32 v[222:223], v[222:223], v[154:155]
	v_mfma_f32_16x16x4_f32 v[240:243], v94, v214, v[240:243]
	ds_read_b64 v[186:187], v35
	ds_read_b64 v[190:191], v35 offset:1024
	v_mfma_f32_16x16x4_f32 v[244:247], v95, v215, v[244:247]
	ds_read_b64 v[194:195], v35 offset:2048
	ds_read_b64 v[198:199], v35 offset:3072
	v_mfma_f32_16x16x4_f32 v[240:243], v96, v216, v[240:243]
	ds_read_b64 v[184:185], v27
	ds_read_b64 v[188:189], v27 offset:1024
	ds_read_b64 v[132:133], v32 offset:9984
	v_mfma_f32_16x16x4_f32 v[244:247], v97, v217, v[244:247]
	ds_read_b64 v[134:135], v33 offset:9984
	ds_read_b32 v38, v239 offset:6144
	ds_read_b64 v[192:193], v27 offset:2048
	v_mfma_f32_16x16x4_f32 v[240:243], v98, v218, v[240:243]
	ds_read_b64 v[196:197], v27 offset:3072
	ds_read_b32 v39, v239 offset:6400
	ds_read_b128 v[140:143], v26 offset:9984
	v_mfma_f32_16x16x4_f32 v[244:247], v99, v219, v[244:247]
	ds_read_b128 v[144:147], v26 offset:11008
	ds_read_b128 v[148:151], v26 offset:12032
	ds_read_b128 v[152:155], v26 offset:13056
	v_mfma_f32_16x16x4_f32 v[240:243], v100, v220, v[240:243]
	ds_read_b32 v156, v29 offset:9988
	ds_read_b32 v157, v29 offset:10060
	ds_read_b64 v[158:159], v29 offset:9992
	v_mfma_f32_16x16x4_f32 v[244:247], v101, v221, v[244:247]
	ds_read_b64 v[160:161], v29 offset:10024
	ds_read_b32 v178, v31 offset:9988
	ds_read_b32 v179, v31 offset:10060
	v_mfma_f32_16x16x4_f32 v[240:243], v102, v222, v[240:243]
	ds_read_b64 v[180:181], v31 offset:9992
	ds_read_b64 v[182:183], v31 offset:10024
	ds_read_b64 v[162:163], v30 offset:9984
	v_mfma_f32_16x16x4_f32 v[244:247], v103, v223, v[244:247]
	ds_read_b64 v[164:165], v30 offset:10016
	ds_read_b64 v[166:167], v30 offset:10048
	ds_read_b64 v[168:169], v30 offset:10080
	ds_read_b64 v[170:171], v30 offset:9992
	ds_read_b64 v[172:173], v30 offset:10024
	ds_read_b64 v[174:175], v30 offset:10056
	ds_read_b64 v[176:177], v30 offset:10088
	s_waitcnt lgkmcnt(15)
	v_mfma_f32_16x16x4_f32 v[208:211], v186, v36, v[208:211]
	v_mfma_f32_16x16x4_f32 v[212:215], v190, v36, v[212:215]
	v_pk_add_f32 v[240:241], v[240:241], v[244:245]
	v_pk_add_f32 v[242:243], v[242:243], v[246:247]
	v_fmac_f32_e32 v241, v104, v240
	v_mfma_f32_16x16x4_f32 v[216:219], v194, v36, v[216:219]
	v_pk_fma_f32 v[242:243], v[106:107], v[240:241], v[242:243] op_sel:[0,0,0] op_sel_hi:[1,0,1]
	v_pk_fma_f32 v[242:243], v[108:109], v[240:241], v[242:243] op_sel:[0,1,0] op_sel_hi:[1,1,1]
	v_fmac_f32_e32 v243, v105, v242
	v_mfma_f32_16x16x4_f32 v[72:75], v132, v38, 0
	ds_bpermute_b32 v204, v232, v240
	ds_bpermute_b32 v205, v232, v241
	ds_bpermute_b32 v206, v232, v242
	v_mfma_f32_16x16x4_f32 v[72:75], v133, v39, v[72:75]
	ds_bpermute_b32 v207, v232, v243
	s_waitcnt lgkmcnt(2)
	v_pk_fma_f32 v[240:241], v[110:111], v[204:205], v[240:241] op_sel:[0,0,0] op_sel_hi:[1,0,1]
	v_pk_fma_f32 v[240:241], v[112:113], v[204:205], v[240:241] op_sel:[0,1,0] op_sel_hi:[1,1,1]
	v_mfma_f32_16x16x4_f32 v[220:223], v198, v36, v[220:223]
	s_waitcnt lgkmcnt(0)
	v_pk_fma_f32 v[240:241], v[114:115], v[206:207], v[240:241] op_sel:[0,0,0] op_sel_hi:[1,0,1]
	v_pk_fma_f32 v[240:241], v[116:117], v[206:207], v[240:241] op_sel:[0,1,0] op_sel_hi:[1,1,1]
	v_pk_fma_f32 v[242:243], v[118:119], v[204:205], v[242:243] op_sel:[0,0,0] op_sel_hi:[1,0,1]
	v_mfma_f32_16x16x4_f32 v[208:211], v187, v37, v[208:211]
	v_pk_fma_f32 v[242:243], v[120:121], v[204:205], v[242:243] op_sel:[0,1,0] op_sel_hi:[1,1,1]
	v_pk_fma_f32 v[242:243], v[122:123], v[206:207], v[242:243] op_sel:[0,0,0] op_sel_hi:[1,0,1]
	v_pk_fma_f32 v[242:243], v[124:125], v[206:207], v[242:243] op_sel:[0,1,0] op_sel_hi:[1,1,1]
	v_mfma_f32_16x16x4_f32 v[212:215], v191, v37, v[212:215]
	v_fmac_f32_e32 v241, v126, v240
	v_pk_fma_f32 v[242:243], v[128:129], v[240:241], v[242:243] op_sel:[0,0,0] op_sel_hi:[1,0,1]
	v_pk_fma_f32 v[242:243], v[130:131], v[240:241], v[242:243] op_sel:[0,1,0] op_sel_hi:[1,1,1]
	v_mfma_f32_16x16x4_f32 v[216:219], v195, v37, v[216:219]
	v_fmac_f32_e32 v243, v127, v242
	v_mov_b32_e32 v252, v240
	v_mov_b32_e32 v253, v241
	v_mfma_f32_16x16x4_f32 v[220:223], v199, v37, v[220:223]
	v_mov_b32_e32 v254, v242
	v_mov_b32_e32 v255, v243
	s_nop 0
	v_permlane32_swap_b32_e32 v252, v254
	v_permlane32_swap_b32_e32 v253, v255
	s_nop 0
	v_mfma_f32_16x16x4_f32 v[248:251], v82, v252, v[240:243]
	v_mfma_f32_16x16x4_f32 v[248:251], v83, v253, v[248:251]
	v_mfma_f32_16x16x4_f32 v[208:211], v184, v252, v[208:211]
	ds_read_b128 v[88:91], v28
	v_mfma_f32_16x16x4_f32 v[212:215], v188, v252, v[212:215]
	ds_read_b128 v[92:95], v28 offset:64
	v_mfma_f32_16x16x4_f32 v[216:219], v192, v252, v[216:219]
	ds_read_b128 v[96:99], v28 offset:128
	v_mfma_f32_16x16x4_f32 v[220:223], v196, v252, v[220:223]
	ds_read_b128 v[100:103], v28 offset:192
	v_mfma_f32_16x16x4_f32 v[208:211], v185, v253, v[208:211]
	s_mov_b64 exec, s[98:99]
	ds_write_b32 v231, v248 offset:4096
	ds_write_b32 v231, v249 offset:4352
	ds_write_b32 v231, v250 offset:4608
	ds_write_b32 v231, v251 offset:4864
	s_mov_b64 exec, -1
	v_mfma_f32_16x16x4_f32 v[212:215], v189, v253, v[212:215]
	v_mfma_f32_16x16x4_f32 v[216:219], v193, v253, v[216:219]
	v_mfma_f32_16x16x4_f32 v[220:223], v197, v253, v[220:223]
	s_waitcnt lgkmcnt(7)
	v_pk_mul_f32 v[208:209], v[208:209], v[88:89]
	v_pk_mul_f32 v[210:211], v[210:211], v[90:91]
	s_nop 0
	v_mfma_f32_16x16x4_f32 v[72:75], v140, v208, v[72:75]
	s_waitcnt lgkmcnt(6)
	v_pk_mul_f32 v[212:213], v[212:213], v[92:93]
	v_mfma_f32_16x16x4_f32 v[244:247], v141, v209, 0
	v_pk_mul_f32 v[214:215], v[214:215], v[94:95]
	v_mfma_f32_16x16x4_f32 v[72:75], v142, v210, v[72:75]
	s_waitcnt lgkmcnt(5)
	v_pk_mul_f32 v[216:217], v[216:217], v[96:97]
	v_mfma_f32_16x16x4_f32 v[244:247], v143, v211, v[244:247]
	v_pk_mul_f32 v[218:219], v[218:219], v[98:99]
	v_mfma_f32_16x16x4_f32 v[72:75], v144, v212, v[72:75]
	s_waitcnt lgkmcnt(4)
	v_pk_mul_f32 v[220:221], v[220:221], v[100:101]
	v_mfma_f32_16x16x4_f32 v[244:247], v145, v213, v[244:247]
	v_pk_mul_f32 v[222:223], v[222:223], v[102:103]
	v_mfma_f32_16x16x4_f32 v[72:75], v146, v214, v[72:75]
	ds_read_b64 v[186:187], v35 offset:9984
	ds_read_b64 v[190:191], v35 offset:11008
	v_mfma_f32_16x16x4_f32 v[244:247], v147, v215, v[244:247]
	ds_read_b64 v[194:195], v35 offset:12032
	ds_read_b64 v[198:199], v35 offset:13056
	v_mfma_f32_16x16x4_f32 v[72:75], v148, v216, v[72:75]
	ds_read_b64 v[184:185], v27 offset:9984
	ds_read_b64 v[188:189], v27 offset:11008
	v_mfma_f32_16x16x4_f32 v[244:247], v149, v217, v[244:247]
	ds_read_b64 v[192:193], v27 offset:12032
	ds_read_b64 v[196:197], v27 offset:13056
	v_mfma_f32_16x16x4_f32 v[72:75], v150, v218, v[72:75]
	v_mfma_f32_16x16x4_f32 v[244:247], v151, v219, v[244:247]
	v_mfma_f32_16x16x4_f32 v[72:75], v152, v220, v[72:75]
	v_mfma_f32_16x16x4_f32 v[244:247], v153, v221, v[244:247]
	v_mfma_f32_16x16x4_f32 v[72:75], v154, v222, v[72:75]
	v_mfma_f32_16x16x4_f32 v[244:247], v155, v223, v[244:247]
	s_waitcnt lgkmcnt(7)
	v_mfma_f32_16x16x4_f32 v[208:211], v186, v38, v[208:211]
	s_waitcnt lgkmcnt(6)
	v_mfma_f32_16x16x4_f32 v[212:215], v190, v38, v[212:215]
	v_pk_add_f32 v[72:73], v[72:73], v[244:245]
	v_pk_add_f32 v[74:75], v[74:75], v[246:247]
	v_fmac_f32_e32 v73, v156, v72
	s_waitcnt lgkmcnt(5)
	v_mfma_f32_16x16x4_f32 v[216:219], v194, v38, v[216:219]
	v_pk_fma_f32 v[74:75], v[158:159], v[72:73], v[74:75] op_sel:[0,0,0] op_sel_hi:[1,0,1]
	v_pk_fma_f32 v[74:75], v[160:161], v[72:73], v[74:75] op_sel:[0,1,0] op_sel_hi:[1,1,1]
	v_fmac_f32_e32 v75, v157, v74
	s_waitcnt lgkmcnt(4)
	v_mfma_f32_16x16x4_f32 v[220:223], v198, v38, v[220:223]
	ds_bpermute_b32 v204, v232, v72
	ds_bpermute_b32 v205, v232, v73
	ds_bpermute_b32 v206, v232, v74
	v_mfma_f32_16x16x4_f32 v[208:211], v187, v39, v[208:211]
	ds_bpermute_b32 v207, v232, v75
	s_waitcnt lgkmcnt(2)
	v_pk_fma_f32 v[72:73], v[162:163], v[204:205], v[72:73] op_sel:[0,0,0] op_sel_hi:[1,0,1]
	v_pk_fma_f32 v[72:73], v[164:165], v[204:205], v[72:73] op_sel:[0,1,0] op_sel_hi:[1,1,1]
	v_mfma_f32_16x16x4_f32 v[212:215], v191, v39, v[212:215]
	s_waitcnt lgkmcnt(0)
	v_pk_fma_f32 v[72:73], v[166:167], v[206:207], v[72:73] op_sel:[0,0,0] op_sel_hi:[1,0,1]
	v_pk_fma_f32 v[72:73], v[168:169], v[206:207], v[72:73] op_sel:[0,1,0] op_sel_hi:[1,1,1]
	v_pk_fma_f32 v[74:75], v[170:171], v[204:205], v[74:75] op_sel:[0,0,0] op_sel_hi:[1,0,1]
	v_mfma_f32_16x16x4_f32 v[216:219], v195, v39, v[216:219]
	v_pk_fma_f32 v[74:75], v[172:173], v[204:205], v[74:75] op_sel:[0,1,0] op_sel_hi:[1,1,1]
	v_pk_fma_f32 v[74:75], v[174:175], v[206:207], v[74:75] op_sel:[0,0,0] op_sel_hi:[1,0,1]
	v_pk_fma_f32 v[74:75], v[176:177], v[206:207], v[74:75] op_sel:[0,1,0] op_sel_hi:[1,1,1]
	v_mfma_f32_16x16x4_f32 v[220:223], v199, v39, v[220:223]
	v_fmac_f32_e32 v73, v178, v72
	v_pk_fma_f32 v[74:75], v[180:181], v[72:73], v[74:75] op_sel:[0,0,0] op_sel_hi:[1,0,1]
	v_pk_fma_f32 v[74:75], v[182:183], v[72:73], v[74:75] op_sel:[0,1,0] op_sel_hi:[1,1,1]
	v_fmac_f32_e32 v75, v179, v74
	v_mov_b32_e32 v252, v72
	v_mov_b32_e32 v253, v73
	v_mov_b32_e32 v254, v74
	v_mov_b32_e32 v255, v75
	s_nop 0
	v_permlane32_swap_b32_e32 v252, v254
	v_permlane32_swap_b32_e32 v253, v255
	s_nop 0
	v_mfma_f32_16x16x4_f32 v[248:251], v134, v252, v[72:75]
	v_mfma_f32_16x16x4_f32 v[248:251], v135, v253, v[248:251]
	v_mfma_f32_16x16x4_f32 v[208:211], v184, v252, v[208:211]
	ds_read_b128 v[140:143], v28 offset:9984
	v_mfma_f32_16x16x4_f32 v[212:215], v188, v252, v[212:215]
	ds_read_b128 v[144:147], v28 offset:10048
	v_mfma_f32_16x16x4_f32 v[216:219], v192, v252, v[216:219]
	ds_read_b128 v[148:151], v28 offset:10112
	v_mfma_f32_16x16x4_f32 v[220:223], v196, v252, v[220:223]
	ds_read_b128 v[152:155], v28 offset:10176
	v_mfma_f32_16x16x4_f32 v[208:211], v185, v253, v[208:211]
	s_mov_b64 exec, s[98:99]
	ds_write_b32 v231, v248 offset:6144
	ds_write_b32 v231, v249 offset:6400
	ds_write_b32 v231, v250 offset:6656
	ds_write_b32 v231, v251 offset:6912
	s_mov_b64 exec, -1
	v_mfma_f32_16x16x4_f32 v[212:215], v189, v253, v[212:215]
	v_mfma_f32_16x16x4_f32 v[216:219], v193, v253, v[216:219]
	v_mfma_f32_16x16x4_f32 v[220:223], v197, v253, v[220:223]
	s_waitcnt lgkmcnt(7)
	v_pk_mul_f32 v[208:209], v[208:209], v[140:141]
	v_pk_mul_f32 v[210:211], v[210:211], v[142:143]
	s_waitcnt lgkmcnt(6)
	v_pk_mul_f32 v[212:213], v[212:213], v[144:145]
	v_pk_mul_f32 v[214:215], v[214:215], v[146:147]
	s_waitcnt lgkmcnt(5)
	v_pk_mul_f32 v[216:217], v[216:217], v[148:149]
	v_pk_mul_f32 v[218:219], v[218:219], v[150:151]
	s_waitcnt lgkmcnt(4)
	s_nop 3
	v_pk_mul_f32 v[220:221], v[220:221], v[152:153]
	v_pk_mul_f32 v[222:223], v[222:223], v[154:155]
	s_branch .LBB0_655

.Lmy_f_nol34:
	s_waitcnt lgkmcnt(0)
	s_bfe_u32 s96, s62, 0x20006
	s_and_b32 s97, s96, 1
	s_mul_i32 s97, s97, 0x2700
	s_mov_b32 s101, 0x1c000
	s_mov_b32 s100, 0x6100
	s_bitcmp0_b32 s65, 0
	s_cselect_b32 s101, 0xe000, s101
	s_cselect_b32 s100, 0x4e00, s100
	s_cmp_gt_u32 s96, 1
	s_cselect_b32 s100, s100, 0
	s_add_i32 s97, s97, s101
	s_add_i32 s97, s97, s100
	ds_read_b32 v80, v198
	ds_read_b32 v81, v198 offset:256
	ds_read_b32 v82, v198 offset:512
	ds_read_b32 v83, v198 offset:768
	ds_read_b32 v84, v198 offset:1024
	ds_read_b32 v85, v198 offset:1280
	ds_read_b32 v86, v198 offset:1536
	ds_read_b32 v87, v198 offset:1792
	ds_read_b32 v88, v198 offset:8192
	ds_read_b32 v89, v198 offset:8448
	ds_read_b32 v90, v198 offset:8704
	ds_read_b32 v91, v198 offset:8960
	ds_read_b32 v92, v198 offset:9216
	ds_read_b32 v93, v198 offset:9472
	ds_read_b32 v94, v198 offset:9728
	ds_read_b32 v95, v198 offset:9984
	ds_read_b32 v96, v198 offset:32768
	ds_read_b32 v97, v198 offset:33024
	ds_read_b32 v98, v198 offset:33280
	ds_read_b32 v99, v198 offset:33536
	ds_read_b32 v100, v198 offset:33792
	ds_read_b32 v101, v198 offset:34048
	ds_read_b32 v102, v198 offset:34304
	ds_read_b32 v103, v198 offset:34560
	s_add_i32 s100, s97, 0x0
	v_add_u32_e32 v76, s100, v200
	v_add_u32_e32 v77, s100, v201
	v_add_u32_e32 v78, s100, v202
	v_add_u32_e32 v79, s100, v203
	s_waitcnt lgkmcnt(15)
	v_mov_b32_e32 v104, v80
	v_mul_f32_e32 v105, v104, v81
	v_mul_f32_e32 v106, v105, v82
	v_mul_f32_e32 v107, v106, v83
	v_mul_f32_e32 v108, v107, v84
	v_mul_f32_e32 v109, v108, v85
	v_mul_f32_e32 v110, v109, v86
	v_mul_f32_e32 v111, v110, v87
	v_mov_b32_e32 v112, v88
	s_waitcnt lgkmcnt(8)
	v_mul_f32_e32 v113, v104, v89
	v_mul_f32_e32 v114, v105, v90
	v_mul_f32_e32 v115, v106, v91
	v_mul_f32_e32 v116, v107, v92
	v_mul_f32_e32 v117, v108, v93
	v_mul_f32_e32 v118, v109, v94
	v_mul_f32_e32 v119, v110, v95
	s_waitcnt lgkmcnt(0)
	v_mul_f32_e32 v120, v104, v96
	v_mul_f32_e32 v121, v105, v97
	v_mul_f32_e32 v122, v106, v98
	v_mul_f32_e32 v123, v107, v99
	v_mul_f32_e32 v124, v108, v100
	v_mul_f32_e32 v125, v109, v101
	v_mul_f32_e32 v126, v110, v102
	v_mul_f32_e32 v127, v111, v103
	ds_write_b32 v76, v112
	ds_write_b32 v77, v113
	ds_write_b32 v78, v114
	ds_write_b32 v79, v115
	ds_write_b32 v76, v116 offset:64
	ds_write_b32 v77, v117 offset:64
	ds_write_b32 v78, v118 offset:64
	ds_write_b32 v79, v119 offset:64
	ds_write_b32 v76, v120 offset:128
	ds_write_b32 v77, v121 offset:128
	ds_write_b32 v78, v122 offset:128
	ds_write_b32 v79, v123 offset:128
	ds_write_b32 v76, v124 offset:192
	ds_write_b32 v77, v125 offset:192
	ds_write_b32 v78, v126 offset:192
	ds_write_b32 v79, v127 offset:192
	s_waitcnt lgkmcnt(0)
	ds_read_b32 v88, v198 offset:16384
	ds_read_b32 v89, v198 offset:16640
	ds_read_b32 v90, v198 offset:16896
	ds_read_b32 v91, v198 offset:17152
	ds_read_b32 v92, v198 offset:17408
	ds_read_b32 v93, v198 offset:17664
	ds_read_b32 v94, v198 offset:17920
	ds_read_b32 v95, v198 offset:18176
	ds_read_b32 v96, v198 offset:24576
	ds_read_b32 v97, v198 offset:24832
	ds_read_b32 v98, v198 offset:25088
	ds_read_b32 v99, v198 offset:25344
	ds_read_b32 v100, v198 offset:25600
	ds_read_b32 v101, v198 offset:25856
	ds_read_b32 v102, v198 offset:26112
	ds_read_b32 v103, v198 offset:26368
	s_add_i32 s101, s97, 0x1000
	v_add_u32_e32 v74, s101, v204
	s_add_i32 s101, s97, 0x2000
	v_add_u32_e32 v75, s101, v205
	v_rcp_f32_e32 v112, v104
	v_rcp_f32_e32 v113, v105
	v_rcp_f32_e32 v114, v106
	v_rcp_f32_e32 v115, v107
	v_rcp_f32_e32 v116, v108
	v_rcp_f32_e32 v117, v109
	v_rcp_f32_e32 v118, v110
	v_rcp_f32_e32 v119, v111
	s_waitcnt lgkmcnt(7)
	v_mul_f32_e32 v120, v112, v96
	s_waitcnt lgkmcnt(6)
	v_mul_f32_e32 v121, v113, v97
	s_waitcnt lgkmcnt(5)
	v_mul_f32_e32 v122, v114, v98
	s_waitcnt lgkmcnt(4)
	v_mul_f32_e32 v123, v115, v99
	s_waitcnt lgkmcnt(3)
	v_mul_f32_e32 v124, v116, v100
	s_waitcnt lgkmcnt(1)
	v_mul_f32_e32 v125, v117, v101
	v_mul_f32_e32 v126, v118, v102
	s_waitcnt lgkmcnt(0)
	v_mul_f32_e32 v127, v119, v103
	v_mul_f32_e32 v112, v112, v88
	v_mul_f32_e32 v113, v113, v89
	v_mul_f32_e32 v114, v114, v90
	v_mul_f32_e32 v115, v115, v91
	v_mul_f32_e32 v116, v116, v92
	v_mul_f32_e32 v117, v117, v93
	v_mul_f32_e32 v118, v118, v94
	v_mul_f32_e32 v119, v119, v95
	ds_write_b128 v74, v[112:115]
	ds_write_b128 v74, v[116:119] offset:256
	ds_write_b128 v74, v[120:123] offset:512
	ds_write_b128 v74, v[124:127] offset:768
	ds_write_b32 v75, v111
	s_waitcnt lgkmcnt(0)
	s_bfe_u32 s96, s62, 0x20006
	s_and_b32 s97, s96, 1
	s_mul_i32 s97, s97, 0x2700
	s_mov_b32 s101, 0x1c000
	s_mov_b32 s100, 0x6100
	s_bitcmp0_b32 s65, 0
	s_cselect_b32 s101, 0xe000, s101
	s_cselect_b32 s100, 0x4e00, s100
	s_cmp_gt_u32 s96, 1
	s_cselect_b32 s100, s100, 0
	s_add_i32 s97, s97, s101
	s_add_i32 s97, s97, s100
	s_mov_b32 s96, s97
	s_add_i32 s101, s96, 0x1000
	v_add_u32_e32 v78, s101, v206
	v_add_u32_e32 v79, s96, v207
	ds_read_b128 v[96:99], v79
	ds_read_b128 v[100:103], v79 offset:1024
	ds_read_b128 v[104:107], v79 offset:2048
	ds_read_b128 v[108:111], v79 offset:3072
	ds_read_b32 v80, v78
	ds_read_b32 v81, v78 offset:16
	ds_read_b32 v82, v78 offset:32
	ds_read_b32 v83, v78 offset:48
	ds_read_b32 v84, v78 offset:1024
	ds_read_b32 v85, v78 offset:1040
	ds_read_b32 v86, v78 offset:1056
	ds_read_b32 v87, v78 offset:1072
	ds_read_b32 v88, v78 offset:2048
	ds_read_b32 v89, v78 offset:2064
	ds_read_b32 v90, v78 offset:2080
	ds_read_b32 v91, v78 offset:2096
	ds_read_b32 v92, v78 offset:3072
	ds_read_b32 v93, v78 offset:3088
	ds_read_b32 v94, v78 offset:3104
	ds_read_b32 v95, v78 offset:3120
	v_add_u32_e32 v74, s96, v205
	ds_write_b32 v74, v235 offset:9728
	s_waitcnt lgkmcnt(15)
	v_mfma_f32_16x16x4_f32 v[244:247], v80, v96, 0
	v_mfma_f32_16x16x4_f32 v[240:243], v81, v97, 0
	s_waitcnt lgkmcnt(14)
	v_mfma_f32_16x16x4_f32 v[244:247], v82, v98, v[244:247]
	s_waitcnt lgkmcnt(13)
	v_mfma_f32_16x16x4_f32 v[240:243], v83, v99, v[240:243]
	s_waitcnt lgkmcnt(12)
	v_mfma_f32_16x16x4_f32 v[244:247], v84, v100, v[244:247]
	s_waitcnt lgkmcnt(11)
	v_mfma_f32_16x16x4_f32 v[240:243], v85, v101, v[240:243]
	s_waitcnt lgkmcnt(10)
	v_mfma_f32_16x16x4_f32 v[244:247], v86, v102, v[244:247]
	s_waitcnt lgkmcnt(9)
	v_mfma_f32_16x16x4_f32 v[240:243], v87, v103, v[240:243]
	s_waitcnt lgkmcnt(7)
	v_mfma_f32_16x16x4_f32 v[244:247], v88, v104, v[244:247]
	v_mfma_f32_16x16x4_f32 v[240:243], v89, v105, v[240:243]
	s_waitcnt lgkmcnt(4)
	v_mfma_f32_16x16x4_f32 v[244:247], v90, v106, v[244:247]
	v_mfma_f32_16x16x4_f32 v[240:243], v91, v107, v[240:243]
	v_mfma_f32_16x16x4_f32 v[244:247], v92, v108, v[244:247]
	s_waitcnt lgkmcnt(1)
	v_mfma_f32_16x16x4_f32 v[240:243], v93, v109, v[240:243]
	v_mfma_f32_16x16x4_f32 v[244:247], v94, v110, v[244:247]
	v_mfma_f32_16x16x4_f32 v[240:243], v95, v111, v[240:243]
	s_nop 9
	v_add_f32_e32 v244, v244, v240
	v_add_f32_e32 v245, v245, v241
	v_add_f32_e32 v246, v246, v242
	v_add_f32_e32 v247, v247, v243
	v_mul_f32_e32 v128, v244, v208
	v_mul_f32_e32 v129, v245, v209
	v_mul_f32_e32 v130, v246, v210
	v_mul_f32_e32 v131, v247, v211
	ds_write_b128 v79, v[128:131] offset:8448
	v_add_u32_e32 v75, s96, v216
	v_mul_f32_e32 v132, v244, v212
	v_mul_f32_e32 v133, v245, v213
	v_mul_f32_e32 v134, v246, v214
	v_mul_f32_e32 v135, v247, v215
	s_mov_b64 exec, 0x00ff00ff
	ds_write_b32 v75, v132 offset:9472
	ds_write_b32 v75, v133 offset:9504
	ds_write_b32 v75, v134 offset:9536
	ds_write_b32 v75, v135 offset:9568
	s_mov_b64 exec, -1
	s_setprio 0
	s_branch .LBB0_655
	s_nop 0
	s_nop 0
	s_nop 0
	s_nop 0
	s_nop 0
	s_nop 0
	s_nop 0
	s_nop 0
	s_nop 0
	s_nop 0
	s_nop 0
	s_nop 0
	s_nop 0
	s_nop 0
	s_nop 0
	s_nop 0
	s_nop 0
	s_nop 0
	s_nop 0
	s_nop 0
	s_nop 0
	s_nop 0
	s_nop 0
	s_nop 0
	s_nop 0
	s_nop 0
	s_nop 0
	s_nop 0
	s_nop 0
	s_nop 0
	s_nop 0
	s_nop 0
	s_nop 0
	s_nop 0
	s_nop 0
	s_nop 0
	s_nop 0
	s_nop 0
	s_nop 0
	s_nop 0
	s_nop 0
	s_nop 0
	s_nop 0
	s_nop 0
	s_nop 0
	s_nop 0
	s_nop 0
	s_nop 0
	s_nop 0
	s_nop 0
	s_nop 0
	s_nop 0
	s_nop 0
	s_nop 0
	s_nop 0
	s_nop 0
	s_nop 0
